# attention importance pass: LDS float atomics replaced by ds_bpermute neighbour exchange plus plain writes; table rows padded to 65 floats
# speedup vs baseline: 1.0344x; 1.0208x over previous
; #define LAS __attribute__((address_space(3)))
; __device__ __forceinline__ void attn_item(const bf16_t* Q, const bf16_t* KV, const bf16_t* KC, const bf16_t* VCT, const float* NG, bf16_t* OATT,
;                                           int bg, int tb, LAS unsigned char* lds) {
;     int tid = threadIdx.x; asm volatile("" : "+v"(tid));
;     const int w = __builtin_amdgcn_readfirstlane(tid >> 6), lane = tid & 63, r = w >> 1, qh = w & 1; int ql = lane & 15, g = lane >> 4;
;     asm volatile("" : "+v"(ql), "+v"(g));
;     const int b = bg >> 2, gk = bg & 3, h = gk * 4 + r;
;     int qq[2], t[2], row[2];
;     bf16x8 qf[2][4];
; #pragma unroll
;     for (int gp = 0; gp < 2; ++gp) {
;         qq[gp] = 32 * qh + 16 * gp + ql; t[gp] = 64 * tb + qq[gp]; row[gp] = b * SEQ + t[gp];
; #pragma unroll
;         for (int kc = 0; kc < 4; ++kc) qf[gp][kc] = *(const bf16x8*)(Q + (size_t)row[gp] * DM + h * 128 + kc * 32 + g * 8);
;     }
;     if (tb >= 16) { LAS u32x4* z = (LAS u32x4*)(lds + IMP_OFF);
; #pragma unroll
;       for (int i = 0; i < 8; ++i) z[tid + i * 512] = (u32x4){0u, 0u, 0u, 0u}; }
.Lattn_prio_done:
	s_ashr_i32 s15, s14, 7
	s_and_b32 s6, s6, 12
	s_add_i32 s17, s15, s6
	s_lshl_b32 s6, s1, 5
	v_and_b32_e32 v211, 15, v225
	v_bfe_u32 v220, v225, 4, 2
	s_and_b32 s84, s6, 32
	s_lshl_b32 s6, s17, 7
	v_add_u32_e32 v218, s84, v211
	s_lshl_b32 s85, s0, 6
	s_ashr_i32 s7, s6, 31
	v_add_u32_e32 v219, 16, v218
	s_lshl_b64 s[8:9], s[6:7], 1
	v_add_u32_e32 v216, s85, v218
	v_add_u32_e32 v215, s85, v219
	s_add_u32 s6, s78, s8
	v_lshlrev_b32_e32 v148, 3, v220
	v_add_u32_e32 v162, s61, v216
	v_add_u32_e32 v158, s61, v215
	s_addc_u32 s7, s79, s9
	v_ashrrev_i32_e32 v149, 31, v148
	v_ashrrev_i32_e32 v163, 31, v162
	v_ashrrev_i32_e32 v159, 31, v158
	v_lshl_add_u64 v[2:3], v[148:149], 1, s[6:7]
	v_lshlrev_b64 v[160:161], 12, v[162:163]
	v_lshlrev_b64 v[154:155], 12, v[158:159]
	v_lshl_add_u64 v[16:17], v[2:3], 0, v[160:161]
	v_lshl_add_u64 v[2:3], v[2:3], 0, v[154:155]
	global_load_dwordx4 v[4:7], v[16:17], off
	global_load_dwordx4 v[8:11], v[16:17], off offset:64
	global_load_dwordx4 v[12:15], v[16:17], off offset:128
	s_nop 0
	global_load_dwordx4 v[16:19], v[16:17], off offset:192
	s_nop 0
	global_load_dwordx4 v[20:23], v[2:3], off
	global_load_dwordx4 v[24:27], v[2:3], off offset:64
	global_load_dwordx4 v[28:31], v[2:3], off offset:128
	global_load_dwordx4 v[32:35], v[2:3], off offset:192
	s_cmp_gt_i32 s0, 15
	s_cselect_b64 s[6:7], -1, 0
	s_cmp_lt_i32 s0, 16
	s_cbranch_scc1 .LBB0_959
	v_lshl_add_u32 v0, v225, 4, 0
	v_add_u32_e32 v0, 0x11800, v0
	ds_write_b128 v0, v[240:243]
	ds_write_b128 v0, v[240:243] offset:8192
	ds_write_b128 v0, v[240:243] offset:16384
	ds_write_b128 v0, v[240:243] offset:24576
	ds_write_b128 v0, v[240:243] offset:32768
	ds_write_b128 v0, v[240:243] offset:40960
	ds_write_b128 v0, v[240:243] offset:49152
	ds_write_b128 v0, v[240:243] offset:57344
	v_add_u32_e32 v0, 0x10000, v0
	v_cmp_gt_u32_e64 s[10:11], 64, v225
	s_nop 1
	s_and_saveexec_b64 s[10:11], s[10:11]
	ds_write_b128 v0, v[240:243]
	s_or_b64 exec, exec, s[10:11]

; __device__ __forceinline__ unsigned cvt_pk_bf16(float lo, float hi) { unsigned r; asm volatile("v_cvt_pk_bf16_f32 %0, %1, %2" : "=v"(r) : "v"(lo), "v"(hi)); return r; }
; __device__ __forceinline__ void attn_item(const bf16_t* Q, const bf16_t* KV, const bf16_t* KC, const bf16_t* VCT, const float* NG, bf16_t* OATT,
;                                           int bg, int tb, LAS unsigned char* lds) {
;     ...
; #pragma unroll
;         for (int gp = 0; gp < 2; ++gp) {
;             invc[gp] = l[gp] > 0.f ? 1.0f / l[gp] : 0.f;
;             const float sc = NG[(size_t)row[gp] * 48 + h * 3 + 0] * invc[gp];
; #pragma unroll
;             for (int dt = 0; dt < 8; ++dt) { const f32x4 v = o[gp][dt] * sc; u32x2 wv; wv.x = cvt_pk_bf16(v[0], v[1]); wv.y = cvt_pk_bf16(v[2], v[3]);
;                 *(u32x2*)(OATT + (size_t)row[gp] * DM + h * 128 + dt * 16 + 4 * g) = wv; }
;         }
;     }
;     unsigned long long selm[2] = {~0ull, ~0ull};
;     if (tb >= 16) {
;     {
;         StageRegs R; stage_load<true, false>(R, KCg, VCg, 256, 0, tid);
;         stage_store<true, false>(R, lds, tid);
;         __syncthreads();
.LBB0_970:
	s_mul_i32 s10, s17, 3
	s_ashr_i32 s11, s10, 31
	s_lshl_b64 s[10:11], s[10:11], 2
	s_add_u32 s10, s89, s10
	s_addc_u32 s11, s38, s11
	s_waitcnt vmcnt(2)
	v_mov_b64_e32 v[102:103], s[10:11]
	v_mad_i64_i32 v[162:163], s[10:11], v162, s97, v[102:103]
	global_load_dword v106, v[162:163], off
	v_mov_b32_e32 v100, v173
	v_mov_b32_e32 v104, v172
	s_nop 0
	v_permlane32_swap_b32_e32 v173, v100
	v_permlane32_swap_b32_e32 v172, v104
	v_add_f32_e32 v101, v173, v100
	v_add_f32_e32 v100, v172, v104
	v_mov_b32_e32 v105, v101
	v_mov_b32_e32 v104, v100
	s_nop 0
	v_permlane16_swap_b32_e32 v101, v105
	v_permlane16_swap_b32_e32 v100, v104
	v_pk_add_f32 v[100:101], v[100:101], v[104:105]
	s_add_u32 s8, s74, s8
	v_div_scale_f32 v104, s[10:11], v101, v101, 1.0
	v_rcp_f32_e32 v107, v104
	v_div_scale_f32 v105, vcc, 1.0, v101, 1.0
	v_ashrrev_i32_e32 v157, 31, v156
	s_waitcnt vmcnt(2)
	v_fma_f32 v108, -v104, v107, 1.0
	v_fmac_f32_e32 v107, v108, v107
	v_mul_f32_e32 v108, v105, v107
	v_fma_f32 v109, -v104, v108, v105
	v_fmac_f32_e32 v108, v109, v107
	v_fma_f32 v104, -v104, v108, v105
	v_div_fmas_f32 v104, v104, v107, v108
	v_div_fixup_f32 v104, v104, v101, 1.0
	v_cmp_lt_f32_e32 vcc, 0, v101
	s_addc_u32 s9, s75, s9
	v_mad_i64_i32 v[158:159], s[10:11], v158, s97, v[102:103]
	v_cndmask_b32_e32 v101, 0, v104, vcc
	v_lshl_add_u64 v[102:103], v[156:157], 1, s[8:9]
	v_lshl_add_u64 v[160:161], v[102:103], 0, v[160:161]
	v_mov_b64_e32 v[172:173], -1
	v_lshl_add_u64 v[154:155], v[102:103], 0, v[154:155]
	v_mov_b64_e32 v[174:175], -1
	s_waitcnt vmcnt(0)
	v_mul_f32_e32 v104, v106, v101
	v_pk_mul_f32 v[96:97], v[96:97], v[104:105] op_sel_hi:[1,0]
	v_pk_mul_f32 v[92:93], v[92:93], v[104:105] op_sel_hi:[1,0]
	v_pk_mul_f32 v[88:89], v[88:89], v[104:105] op_sel_hi:[1,0]
	v_pk_mul_f32 v[84:85], v[84:85], v[104:105] op_sel_hi:[1,0]
	v_pk_mul_f32 v[80:81], v[80:81], v[104:105] op_sel_hi:[1,0]
	v_pk_mul_f32 v[76:77], v[76:77], v[104:105] op_sel_hi:[1,0]
	v_pk_mul_f32 v[72:73], v[72:73], v[104:105] op_sel_hi:[1,0]
	v_pk_mul_f32 v[68:69], v[68:69], v[104:105] op_sel_hi:[1,0]
	v_pk_mul_f32 v[98:99], v[98:99], v[104:105] op_sel_hi:[1,0]
	v_pk_mul_f32 v[94:95], v[94:95], v[104:105] op_sel_hi:[1,0]
	v_pk_mul_f32 v[90:91], v[90:91], v[104:105] op_sel_hi:[1,0]
	v_pk_mul_f32 v[86:87], v[86:87], v[104:105] op_sel_hi:[1,0]
	v_pk_mul_f32 v[82:83], v[82:83], v[104:105] op_sel_hi:[1,0]
	v_pk_mul_f32 v[78:79], v[78:79], v[104:105] op_sel_hi:[1,0]
	v_pk_mul_f32 v[74:75], v[74:75], v[104:105] op_sel_hi:[1,0]
	v_pk_mul_f32 v[70:71], v[70:71], v[104:105] op_sel_hi:[1,0]
	v_cvt_pk_bf16_f32 v96, v96, v97
	v_cvt_pk_bf16_f32 v97, v98, v99
	global_store_dwordx2 v[160:161], v[96:97], off
	v_cvt_pk_bf16_f32 v92, v92, v93
	v_cvt_pk_bf16_f32 v93, v94, v95
	global_store_dwordx2 v[160:161], v[92:93], off offset:32
	v_cvt_pk_bf16_f32 v88, v88, v89
	v_cvt_pk_bf16_f32 v89, v90, v91
	global_store_dwordx2 v[160:161], v[88:89], off offset:64
	v_cvt_pk_bf16_f32 v84, v84, v85
	v_cvt_pk_bf16_f32 v85, v86, v87
	global_store_dwordx2 v[160:161], v[84:85], off offset:96
	v_cvt_pk_bf16_f32 v80, v80, v81
	v_cvt_pk_bf16_f32 v81, v82, v83
	global_store_dwordx2 v[160:161], v[80:81], off offset:128
	v_cvt_pk_bf16_f32 v76, v76, v77
	v_cvt_pk_bf16_f32 v77, v78, v79
	global_store_dwordx2 v[160:161], v[76:77], off offset:160
	v_cvt_pk_bf16_f32 v72, v72, v73
	v_cvt_pk_bf16_f32 v73, v74, v75
	global_store_dwordx2 v[160:161], v[72:73], off offset:192
	v_cvt_pk_bf16_f32 v68, v68, v69
	v_cvt_pk_bf16_f32 v69, v70, v71
	global_store_dwordx2 v[160:161], v[68:69], off offset:224
	global_load_dword v68, v[158:159], off
	v_div_scale_f32 v69, s[8:9], v100, v100, 1.0
	v_rcp_f32_e32 v70, v69
	v_div_scale_f32 v71, vcc, 1.0, v100, 1.0
	v_add3_u32 v80, 0, v149, v201
	v_fma_f32 v72, -v69, v70, 1.0
	v_fmac_f32_e32 v70, v72, v70
	v_mul_f32_e32 v72, v71, v70
	v_fma_f32 v73, -v69, v72, v71
	v_fmac_f32_e32 v72, v73, v70
	v_fma_f32 v69, -v69, v72, v71
	v_div_fmas_f32 v69, v69, v70, v72
	s_andn2_b64 vcc, exec, s[6:7]
	v_div_fixup_f32 v69, v69, v100, 1.0
	v_cmp_lt_f32_e64 s[6:7], 0, v100
	s_nop 1
	v_cndmask_b32_e64 v73, 0, v69, s[6:7]
	s_waitcnt vmcnt(0)
	v_mul_f32_e32 v68, v73, v68
	v_pk_mul_f32 v[64:65], v[64:65], v[68:69] op_sel_hi:[1,0]
	v_pk_mul_f32 v[60:61], v[60:61], v[68:69] op_sel_hi:[1,0]
	v_pk_mul_f32 v[56:57], v[56:57], v[68:69] op_sel_hi:[1,0]
	v_pk_mul_f32 v[52:53], v[52:53], v[68:69] op_sel_hi:[1,0]
	v_pk_mul_f32 v[48:49], v[48:49], v[68:69] op_sel_hi:[1,0]
	v_pk_mul_f32 v[44:45], v[44:45], v[68:69] op_sel_hi:[1,0]
	v_pk_mul_f32 v[40:41], v[40:41], v[68:69] op_sel_hi:[1,0]
	v_pk_mul_f32 v[36:37], v[36:37], v[68:69] op_sel_hi:[1,0]
	v_pk_mul_f32 v[66:67], v[66:67], v[68:69] op_sel_hi:[1,0]
	v_pk_mul_f32 v[62:63], v[62:63], v[68:69] op_sel_hi:[1,0]
	v_pk_mul_f32 v[58:59], v[58:59], v[68:69] op_sel_hi:[1,0]
	v_pk_mul_f32 v[54:55], v[54:55], v[68:69] op_sel_hi:[1,0]
	v_pk_mul_f32 v[50:51], v[50:51], v[68:69] op_sel_hi:[1,0]
	v_pk_mul_f32 v[46:47], v[46:47], v[68:69] op_sel_hi:[1,0]
	v_pk_mul_f32 v[42:43], v[42:43], v[68:69] op_sel_hi:[1,0]
	v_pk_mul_f32 v[38:39], v[38:39], v[68:69] op_sel_hi:[1,0]
	v_cvt_pk_bf16_f32 v64, v64, v65
	v_cvt_pk_bf16_f32 v65, v66, v67
	global_store_dwordx2 v[154:155], v[64:65], off
	v_cvt_pk_bf16_f32 v60, v60, v61
	v_cvt_pk_bf16_f32 v61, v62, v63
	global_store_dwordx2 v[154:155], v[60:61], off offset:32
	v_cvt_pk_bf16_f32 v56, v56, v57
	v_cvt_pk_bf16_f32 v57, v58, v59
	global_store_dwordx2 v[154:155], v[56:57], off offset:64
	v_cvt_pk_bf16_f32 v52, v52, v53
	v_cvt_pk_bf16_f32 v53, v54, v55
	global_store_dwordx2 v[154:155], v[52:53], off offset:96
	v_cvt_pk_bf16_f32 v48, v48, v49
	v_cvt_pk_bf16_f32 v49, v50, v51
	global_store_dwordx2 v[154:155], v[48:49], off offset:128
	v_cvt_pk_bf16_f32 v44, v44, v45
	v_cvt_pk_bf16_f32 v45, v46, v47
	global_store_dwordx2 v[154:155], v[44:45], off offset:160
	v_cvt_pk_bf16_f32 v40, v40, v41
	v_cvt_pk_bf16_f32 v41, v42, v43
	global_store_dwordx2 v[154:155], v[40:41], off offset:192
	v_cvt_pk_bf16_f32 v36, v36, v37
	v_cvt_pk_bf16_f32 v37, v38, v39
	global_store_dwordx2 v[154:155], v[36:37], off offset:224
	s_cbranch_vccnz .LBB0_1000
	global_load_dwordx4 v[36:39], v[178:179], off
	global_load_dwordx4 v[40:43], v[180:181], off
	s_lshl_b32 s7, s14, 7
	s_mul_i32 s6, s15, 0x4100
	s_and_b32 s7, s7, 0x2000
	s_lshr_b32 s7, s7, 13
	s_mul_i32 s7, s7, 0x2080
	s_add_u32 s6, s6, s7
	v_mul_u32_u24_e32 v44, 0x104, v211
	v_add_u32_e32 v44, s6, v44
	v_and_b32_e32 v72, 63, v225
	s_add_i32 s17, s16, 1
	v_sub_u32_e32 v74, v236, v217
	v_sub_u32_e32 v75, v237, v217
	v_add3_u32 v76, v44, v217, 0
	v_mov_b32_e32 v132, 0
	v_mov_b32_e32 v133, 0
	s_mov_b32 s18, 0
	s_mov_b32 s19, 0
	s_waitcnt vmcnt(1)
	ds_write_b128 v195, v[36:39]
	s_waitcnt vmcnt(0)
	ds_write_b128 v213, v[40:43]
	s_waitcnt lgkmcnt(0)
	s_barrier
	s_branch .LBB0_973

; #define LAS __attribute__((address_space(3)))
; __device__ __forceinline__ void attn_item(const bf16_t* Q, const bf16_t* KV, const bf16_t* KC, const bf16_t* VCT, const float* NG, bf16_t* OATT,
;                                           int bg, int tb, LAS unsigned char* lds) {
;     ...
;         for (int tile = 0; tile <= cmp_hi; ++tile) {
;             const LAS unsigned char* buf = lds + (tile & 1) * BUF_BYTES;
;             if (tile < cmp_hi) stage_load<true, false>(R, KCg, VCg, 256, (tile + 1) * 64, tid);
;             f32x4 s[2][4]; qk_tile2(s, qf, buf, ql, g);
; #pragma unroll
;             for (int gp = 0; gp < 2; ++gp) {
;                 const int rel = ((t[gp] - 31) >> 4) - tile * 64 - 4 * g;
;                 LAS float* imp = (LAS float*)(lds + IMP_OFF) + (r * 64 + qq[gp]) * 64 + 16 * tile + g;
;                 float carry[4];
; #pragma unroll
;                 for (int sub = 0; sub < 4; ++sub) {
;                     f32x4 p4;
; #pragma unroll
;                     for (int e = 0; e < 4; ++e) p4[e] = (sub * 16 + e <= rel) ? __builtin_amdgcn_exp2f(s[gp][sub][e] - mc[gp]) * invc[gp] : 0.f;
;                     atomicAdd((float*)(imp + 4 * sub), (p4[0] + p4[1]) + (p4[2] + 0.5f * p4[3]));
;                     carry[sub] = 0.5f * p4[3];
.LBB0_975:
	s_bitcmp1_b32 s19, 0
	s_cselect_b32 s6, 0x8c00, 0
	v_add_u32_e32 v77, s6, v80
	ds_read_b128 v[44:47], v77
	ds_read_b128 v[48:51], v77 offset:4352
	ds_read_b128 v[52:55], v77 offset:8704
	ds_read_b128 v[56:59], v77 offset:13056
	ds_read_b128 v[86:89], v77 offset:13120
	ds_read_b128 v[90:93], v77 offset:8768
	ds_read_b128 v[94:97], v77 offset:4416
	ds_read_b128 v[102:105], v77 offset:64
	s_waitcnt lgkmcnt(7)
	v_mfma_f32_16x16x32_bf16 v[60:63], v[44:47], v[4:7], 0
	v_cmp_lt_i32_e32 vcc, -1, v74
	v_mfma_f32_16x16x32_bf16 v[44:47], v[44:47], v[20:23], 0
	s_waitcnt lgkmcnt(6)
	v_mfma_f32_16x16x32_bf16 v[64:67], v[48:51], v[4:7], 0
	v_mfma_f32_16x16x32_bf16 v[48:51], v[48:51], v[20:23], 0
	s_waitcnt lgkmcnt(5)
	v_mfma_f32_16x16x32_bf16 v[68:71], v[52:55], v[4:7], 0
	v_mfma_f32_16x16x32_bf16 v[52:55], v[52:55], v[20:23], 0
	s_waitcnt lgkmcnt(4)
	v_mfma_f32_16x16x32_bf16 v[82:85], v[56:59], v[4:7], 0
	v_mfma_f32_16x16x32_bf16 v[56:59], v[56:59], v[20:23], 0
	s_waitcnt lgkmcnt(0)
	v_mfma_f32_16x16x32_bf16 v[60:63], v[102:105], v[8:11], v[60:63]
	v_mfma_f32_16x16x32_bf16 v[44:47], v[102:105], v[24:27], v[44:47]
	v_mfma_f32_16x16x32_bf16 v[64:67], v[94:97], v[8:11], v[64:67]
	v_mfma_f32_16x16x32_bf16 v[48:51], v[94:97], v[24:27], v[48:51]
	v_mfma_f32_16x16x32_bf16 v[68:71], v[90:93], v[8:11], v[68:71]
	v_mfma_f32_16x16x32_bf16 v[52:55], v[90:93], v[24:27], v[52:55]
	v_mfma_f32_16x16x32_bf16 v[82:85], v[86:89], v[8:11], v[82:85]
	v_mfma_f32_16x16x32_bf16 v[56:59], v[86:89], v[24:27], v[56:59]
	ds_read_b128 v[86:89], v77 offset:128
	ds_read_b128 v[90:93], v77 offset:4480
	ds_read_b128 v[94:97], v77 offset:8832
	ds_read_b128 v[102:105], v77 offset:13184
	s_waitcnt lgkmcnt(3)
	v_mfma_f32_16x16x32_bf16 v[60:63], v[86:89], v[12:15], v[60:63]
	v_mfma_f32_16x16x32_bf16 v[44:47], v[86:89], v[28:31], v[44:47]
	s_waitcnt lgkmcnt(2)
	v_mfma_f32_16x16x32_bf16 v[64:67], v[90:93], v[12:15], v[64:67]
	v_mfma_f32_16x16x32_bf16 v[48:51], v[90:93], v[28:31], v[48:51]
	s_waitcnt lgkmcnt(1)
	v_mfma_f32_16x16x32_bf16 v[86:89], v[94:97], v[12:15], v[68:71]
	v_mfma_f32_16x16x32_bf16 v[90:93], v[94:97], v[28:31], v[52:55]
	s_waitcnt lgkmcnt(0)
	v_mfma_f32_16x16x32_bf16 v[82:85], v[102:105], v[12:15], v[82:85]
	v_mfma_f32_16x16x32_bf16 v[94:97], v[102:105], v[28:31], v[56:59]
	ds_read_b128 v[102:105], v77 offset:13248
	ds_read_b128 v[106:109], v77 offset:8896
	ds_read_b128 v[52:55], v77 offset:4544
	ds_read_b128 v[56:59], v77 offset:192
	v_add_u32_e32 v77, s18, v76
	s_waitcnt lgkmcnt(0)
	v_mfma_f32_16x16x32_bf16 v[110:113], v[56:59], v[16:19], v[60:63]
	v_add_u32_e32 v79, 0x11800, v77
	v_mfma_f32_16x16x32_bf16 v[60:63], v[102:105], v[16:19], v[82:85]
	s_nop 5
	v_sub_f32_e32 v78, v110, v223
	v_exp_f32_e32 v78, v78
	v_mfma_f32_16x16x32_bf16 v[68:71], v[52:55], v[16:19], v[64:67]
	v_mul_f32_e32 v78, v101, v78
	v_cndmask_b32_e32 v81, 0, v78, vcc
	v_sub_f32_e32 v78, v111, v223
	v_exp_f32_e32 v78, v78
	v_cmp_lt_i32_e32 vcc, 0, v74
	s_nop 2
	v_sub_f32_e32 v68, v68, v223
	v_exp_f32_e32 v68, v68
	v_mul_f32_e32 v78, v101, v78
	v_cndmask_b32_e32 v82, 0, v78, vcc
	v_sub_f32_e32 v78, v112, v223
	v_exp_f32_e32 v78, v78
	v_cmp_lt_i32_e32 vcc, 1, v74
	v_add_f32_e32 v81, v81, v82
	v_mul_f32_e32 v68, v101, v68
	v_mul_f32_e32 v78, v101, v78
	v_cndmask_b32_e32 v83, 0, v78, vcc
	v_sub_f32_e32 v78, v113, v223
	v_exp_f32_e32 v78, v78
	v_cmp_lt_i32_e32 vcc, 2, v74
	v_mfma_f32_16x16x32_bf16 v[64:67], v[106:109], v[16:19], v[86:89]
	v_sub_f32_e32 v60, v60, v223
	v_mul_f32_e32 v78, v101, v78
	v_mul_f32_e32 v78, 0.5, v78
	v_cndmask_b32_e32 v78, 0, v78, vcc
	v_add_f32_e32 v82, v83, v78
	v_add_f32_e32 v81, v81, v82
	v_cmp_lt_i32_e32 vcc, 15, v74
	v_mov_b32_e32 v116, v81
	v_sub_f32_e32 v64, v64, v223
	v_cndmask_b32_e32 v79, 0, v68, vcc
	v_sub_f32_e32 v68, v69, v223
	v_exp_f32_e32 v68, v68
	v_cmp_lt_i32_e32 vcc, 16, v74
	v_exp_f32_e32 v64, v64
	v_exp_f32_e32 v60, v60
	v_mul_f32_e32 v68, v101, v68
	v_cndmask_b32_e32 v69, 0, v68, vcc
	v_sub_f32_e32 v68, v70, v223
	v_exp_f32_e32 v68, v68
	v_cmp_lt_i32_e32 vcc, 17, v74
	v_add_f32_e32 v69, v79, v69
	v_mul_f32_e32 v64, v101, v64
	v_mul_f32_e32 v68, v101, v68
	v_cndmask_b32_e32 v70, 0, v68, vcc
	v_sub_f32_e32 v68, v71, v223
	v_exp_f32_e32 v68, v68
	v_cmp_lt_i32_e32 vcc, 18, v74
	v_add_u32_e32 v71, 0x11810, v77
	v_mul_f32_e32 v60, v101, v60
	v_mul_f32_e32 v68, v101, v68
	v_mul_f32_e32 v68, 0.5, v68
	v_cndmask_b32_e32 v68, 0, v68, vcc
	v_add_f32_e32 v70, v70, v68
	v_add_f32_e32 v69, v69, v70
	v_cmp_lt_i32_e32 vcc, 31, v74
	v_mov_b32_e32 v117, v69
	v_mfma_f32_16x16x32_bf16 v[56:59], v[56:59], v[32:35], v[44:47]
	v_cndmask_b32_e32 v69, 0, v64, vcc
	v_sub_f32_e32 v64, v65, v223
	v_exp_f32_e32 v64, v64
	v_cmp_lt_i32_e32 vcc, 32, v74
	v_mfma_f32_16x16x32_bf16 v[52:55], v[52:55], v[32:35], v[48:51]
	v_mul_f32_e32 v64, v101, v64
	v_cndmask_b32_e32 v65, 0, v64, vcc
	v_sub_f32_e32 v64, v66, v223
	v_exp_f32_e32 v64, v64
	v_cmp_lt_i32_e32 vcc, 33, v74
	v_add_f32_e32 v65, v69, v65
	v_mfma_f32_16x16x32_bf16 v[48:51], v[106:109], v[32:35], v[90:93]
	v_mul_f32_e32 v64, v101, v64
	v_cndmask_b32_e32 v66, 0, v64, vcc
	v_sub_f32_e32 v64, v67, v223
	v_exp_f32_e32 v64, v64
	v_cmp_lt_i32_e32 vcc, 34, v74
	v_add_u32_e32 v67, 0x11820, v77
	v_mfma_f32_16x16x32_bf16 v[44:47], v[102:105], v[32:35], v[94:97]
	v_mul_f32_e32 v64, v101, v64
	v_mul_f32_e32 v64, 0.5, v64
	v_cndmask_b32_e32 v64, 0, v64, vcc
	v_add_f32_e32 v66, v66, v64
	v_add_f32_e32 v65, v65, v66
	v_cmp_lt_i32_e32 vcc, 47, v74
	v_mov_b32_e32 v118, v65
	s_nop 0
	v_cndmask_b32_e32 v65, 0, v60, vcc
; #define LAS __attribute__((address_space(3)))
; __device__ __forceinline__ void attn_item(const bf16_t* Q, const bf16_t* KV, const bf16_t* KC, const bf16_t* VCT, const float* NG, bf16_t* OATT,
;                                           int bg, int tb, LAS unsigned char* lds) {
;     ...
;             for (int gp = 0; gp < 2; ++gp) {
;                 const int rel = ((t[gp] - 31) >> 4) - tile * 64 - 4 * g;
;                 LAS float* imp = (LAS float*)(lds + IMP_OFF) + (r * 64 + qq[gp]) * 64 + 16 * tile + g;
;                 float carry[4];
; #pragma unroll
;                 for (int sub = 0; sub < 4; ++sub) {
;                     f32x4 p4;
; #pragma unroll
;                     for (int e = 0; e < 4; ++e) p4[e] = (sub * 16 + e <= rel) ? __builtin_amdgcn_exp2f(s[gp][sub][e] - mc[gp]) * invc[gp] : 0.f;
;                     atomicAdd((float*)(imp + 4 * sub), (p4[0] + p4[1]) + (p4[2] + 0.5f * p4[3]));
;                     carry[sub] = 0.5f * p4[3];
;                 }
; #pragma unroll
;                 for (int sub = 0; sub < 4; ++sub) if (16 * tile + 4 * sub + g + 1 < 64) atomicAdd((float*)(imp + 4 * sub + 1), carry[sub]);
;             }
	v_sub_f32_e32 v60, v61, v223
	v_exp_f32_e32 v60, v60
	v_cmp_lt_i32_e32 vcc, 48, v74
	v_mul_f32_e32 v60, v101, v60
	s_nop 0
	v_cndmask_b32_e32 v61, 0, v60, vcc
	v_sub_f32_e32 v60, v62, v223
	v_exp_f32_e32 v60, v60
	v_cmp_lt_i32_e32 vcc, 49, v74
	v_add_f32_e32 v61, v65, v61
	v_mul_f32_e32 v60, v101, v60
	v_cndmask_b32_e32 v62, 0, v60, vcc
	v_sub_f32_e32 v60, v63, v223
	v_exp_f32_e32 v60, v60
	v_cmp_lt_i32_e32 vcc, 50, v74
	v_add_u32_e32 v63, 0x11830, v77
	v_mul_f32_e32 v60, v101, v60
	v_mul_f32_e32 v60, 0.5, v60
	v_cndmask_b32_e32 v60, 0, v60, vcc
	v_add_f32_e32 v62, v62, v60
	v_add_f32_e32 v61, v61, v62
	v_mov_b32_e32 v119, v61
	v_mov_b32_e32 v120, v78
	v_mov_b32_e32 v121, v68
	v_mov_b32_e32 v122, v64
	v_mov_b32_e32 v123, v60
	v_sub_f32_e32 v56, v56, v224
	v_exp_f32_e32 v56, v56
	v_sub_f32_e32 v57, v57, v224
	v_exp_f32_e32 v57, v57
	v_cmp_lt_i32_e64 s[12:13], -1, v75
	v_mul_f32_e32 v56, v73, v56
	v_sub_f32_e32 v52, v52, v224
	v_cndmask_b32_e64 v61, 0, v56, s[12:13]
	v_mul_f32_e32 v56, v73, v57
	v_cmp_lt_i32_e64 s[12:13], 0, v75
	v_sub_f32_e32 v57, v58, v224
	v_exp_f32_e32 v57, v57
	v_cndmask_b32_e64 v58, 0, v56, s[12:13]
	v_sub_f32_e32 v56, v59, v224
	v_exp_f32_e32 v56, v56
	v_mul_f32_e32 v57, v73, v57
	v_cmp_lt_i32_e64 s[12:13], 1, v75
	v_exp_f32_e32 v52, v52
	v_mul_f32_e32 v56, v73, v56
	v_sub_f32_e32 v53, v53, v224
	v_cndmask_b32_e64 v57, 0, v57, s[12:13]
	v_mul_f32_e32 v56, 0.5, v56
	v_cmp_lt_i32_e64 s[12:13], 2, v75
	v_exp_f32_e32 v53, v53
	v_add_f32_e32 v58, v61, v58
	v_cndmask_b32_e64 v56, 0, v56, s[12:13]
	v_add_f32_e32 v57, v57, v56
	v_add_u32_e32 v60, 0x12840, v77
	v_add_f32_e32 v57, v58, v57
	v_mul_f32_e32 v52, v73, v52
	v_cmp_lt_i32_e64 s[12:13], 15, v75
	v_mov_b32_e32 v124, v57
	v_sub_f32_e32 v48, v48, v224
	v_cndmask_b32_e64 v57, 0, v52, s[12:13]
	v_mul_f32_e32 v52, v73, v53
	v_cmp_lt_i32_e64 s[12:13], 16, v75
	v_sub_f32_e32 v53, v54, v224
	v_exp_f32_e32 v53, v53
	v_cndmask_b32_e64 v54, 0, v52, s[12:13]
	v_sub_f32_e32 v52, v55, v224
	v_exp_f32_e32 v52, v52
	v_mul_f32_e32 v53, v73, v53
	v_cmp_lt_i32_e64 s[12:13], 17, v75
	v_exp_f32_e32 v48, v48
	v_mul_f32_e32 v52, v73, v52
	v_sub_f32_e32 v49, v49, v224
	v_cndmask_b32_e64 v53, 0, v53, s[12:13]
	v_mul_f32_e32 v52, 0.5, v52
	v_cmp_lt_i32_e64 s[12:13], 18, v75
	v_exp_f32_e32 v49, v49
	v_add_f32_e32 v54, v57, v54
	v_cndmask_b32_e64 v52, 0, v52, s[12:13]
	v_add_f32_e32 v53, v53, v52
	v_add_u32_e32 v55, 0x12850, v77
	v_add_f32_e32 v53, v54, v53
	v_mul_f32_e32 v48, v73, v48
	v_cmp_lt_i32_e64 s[12:13], 31, v75
	v_mov_b32_e32 v125, v53
	v_sub_f32_e32 v44, v44, v224
	v_cndmask_b32_e64 v53, 0, v48, s[12:13]
	v_mul_f32_e32 v48, v73, v49
	v_cmp_lt_i32_e64 s[12:13], 32, v75
	v_sub_f32_e32 v49, v50, v224
	v_exp_f32_e32 v49, v49
	v_cndmask_b32_e64 v50, 0, v48, s[12:13]
	v_sub_f32_e32 v48, v51, v224
	v_exp_f32_e32 v48, v48
	v_mul_f32_e32 v49, v73, v49
	v_cmp_lt_i32_e64 s[12:13], 33, v75
	v_exp_f32_e32 v44, v44
	v_mul_f32_e32 v48, v73, v48
	v_sub_f32_e32 v45, v45, v224
	v_cndmask_b32_e64 v49, 0, v49, s[12:13]
	v_mul_f32_e32 v48, 0.5, v48
	v_cmp_lt_i32_e64 s[12:13], 34, v75
	v_exp_f32_e32 v45, v45
	v_add_f32_e32 v50, v53, v50
	v_cndmask_b32_e64 v48, 0, v48, s[12:13]
	v_add_f32_e32 v49, v49, v48
	v_add_u32_e32 v51, 0x12860, v77
	v_add_f32_e32 v49, v50, v49
	v_mul_f32_e32 v44, v73, v44
	v_cmp_lt_i32_e64 s[12:13], 47, v75
	v_mov_b32_e32 v126, v49
	s_nop 0
	v_cndmask_b32_e64 v49, 0, v44, s[12:13]
	v_mul_f32_e32 v44, v73, v45
	v_cmp_lt_i32_e64 s[12:13], 48, v75
	v_sub_f32_e32 v45, v46, v224
	v_exp_f32_e32 v45, v45
	v_cndmask_b32_e64 v46, 0, v44, s[12:13]
	v_sub_f32_e32 v44, v47, v224
	v_exp_f32_e32 v44, v44
	v_mul_f32_e32 v45, v73, v45
	v_cmp_lt_i32_e64 s[12:13], 49, v75
	v_add_f32_e32 v46, v49, v46
	v_mul_f32_e32 v44, v73, v44
	v_cndmask_b32_e64 v45, 0, v45, s[12:13]
	v_mul_f32_e32 v44, 0.5, v44
	v_cmp_lt_i32_e64 s[12:13], 50, v75
	v_add_u32_e32 v47, 0x12870, v77
	s_nop 0
	v_cndmask_b32_e64 v44, 0, v44, s[12:13]
	v_add_f32_e32 v45, v45, v44
	v_add_f32_e32 v45, v46, v45
	v_mov_b32_e32 v127, v45
	v_cmp_gt_u32_e64 s[6:7], 16, v72
	v_add_u32_e32 v134, -16, v72
	v_and_b32_e32 v134, 63, v134
	v_lshlrev_b32_e32 v134, 2, v134
	ds_bpermute_b32 v135, v134, v132
	ds_bpermute_b32 v136, v134, v120
	ds_bpermute_b32 v137, v134, v121
	ds_bpermute_b32 v138, v134, v122
	ds_bpermute_b32 v139, v134, v123
	ds_bpermute_b32 v140, v134, v133
	ds_bpermute_b32 v141, v134, v56
	ds_bpermute_b32 v142, v134, v52
	ds_bpermute_b32 v143, v134, v48
	ds_bpermute_b32 v144, v134, v44
	v_add_u32_e32 v145, 0x11800, v77
	s_waitcnt lgkmcnt(0)
	v_mov_b32_e32 v132, v123
	v_mov_b32_e32 v133, v44
	v_cndmask_b32_e64 v135, v136, v135, s[6:7]
	v_cndmask_b32_e64 v136, v137, v136, s[6:7]
	v_cndmask_b32_e64 v137, v138, v137, s[6:7]
	v_cndmask_b32_e64 v138, v139, v138, s[6:7]
	v_cndmask_b32_e64 v140, v141, v140, s[6:7]
	v_cndmask_b32_e64 v141, v142, v141, s[6:7]
	v_cndmask_b32_e64 v142, v143, v142, s[6:7]
	v_cndmask_b32_e64 v143, v144, v143, s[6:7]
	v_add_f32_e32 v135, v116, v135
	v_add_f32_e32 v136, v117, v136
	v_add_f32_e32 v137, v118, v137
	v_add_f32_e32 v138, v119, v138
	v_add_f32_e32 v140, v124, v140
	v_add_f32_e32 v141, v125, v141
	v_add_f32_e32 v142, v126, v142
	v_add_f32_e32 v143, v127, v143
	ds_write_b32 v145, v135
	ds_write_b32 v145, v136 offset:16
	ds_write_b32 v145, v137 offset:32
	ds_write_b32 v145, v138 offset:48
	ds_write_b32 v145, v140 offset:4160
	ds_write_b32 v145, v141 offset:4176
	ds_write_b32 v145, v142 offset:4192
	ds_write_b32 v145, v143 offset:4208
	s_andn2_b64 vcc, exec, s[14:15]
	s_cbranch_vccnz .LBB0_972

; #define LAS __attribute__((address_space(3)))
; __device__ __forceinline__ void attn_item(const bf16_t* Q, const bf16_t* KV, const bf16_t* KC, const bf16_t* VCT, const float* NG, bf16_t* OATT,
;                                           int bg, int tb, LAS unsigned char* lds) {
;     ...
; #pragma unroll 1
;         for (int i = 0; i < 8; ++i) {
;             const int q2 = 8 * w + i;
;             const LAS float* ip = (const LAS float*)(lds + IMP_OFF) + q2 * 64 + lane;
;             float v = ((ip[0] + ip[64 * 64]) + ip[2 * 64 * 64]) + ip[3 * 64 * 64];
;             const bool valid = lane <= tb, forced = (lane == 0) || (lane == tb) || (lane == tb - 1);
;             v = valid ? (forced ? __builtin_inff() : v) : -__builtin_inff();
;             int rank = 0;
; #pragma unroll 8
;             for (int mm = 0; mm < 64; ++mm) { const float vm = __builtin_bit_cast(float, __builtin_amdgcn_readlane(__builtin_bit_cast(int, v), mm)); rank += (vm > v || (vm == v && mm < lane)) ? 1 : 0; }
;             const unsigned long long mask = __ballot(rank < 16);
;             if (lane == 0) *(LAS unsigned long long*)(lds + SELM_OFF + q2 * 8) = mask;
;         }
;     }
;     __syncthreads();
;     selm[0] = *(const LAS unsigned long long*)(lds + SELM_OFF + qq[0] * 8); selm[1] = *(const LAS unsigned long long*)(lds + SELM_OFF + qq[1] * 8);
.Lrank_pair:
	s_add_i32 s17, s16, s1
	s_mul_i32 s22, s17, 0x104
	v_add_u32_e32 v38, s22, v3
	ds_read2st64_b32 v[36:37], v38 offset1:65
	ds_read2st64_b32 v[40:41], v38 offset0:130 offset1:195
	v_add_u32_e32 v39, 0x104, v38
	ds_read2st64_b32 v[42:43], v39 offset1:65
	ds_read2st64_b32 v[44:45], v39 offset0:130 offset1:195
	s_mov_b32 s20, 0
	s_mov_b32 s21, 0
	s_mov_b32 s18, 0x40000000
	s_waitcnt lgkmcnt(2)
	v_add_f32_e32 v36, v36, v37
	v_add_f32_e32 v36, v36, v40
	v_add_f32_e32 v36, v36, v41
	s_waitcnt lgkmcnt(0)
	v_add_f32_e32 v42, v42, v43
	v_add_f32_e32 v42, v42, v44
	v_add_f32_e32 v42, v42, v45
	v_cndmask_b32_e64 v36, v36, v234, s[8:9]
	v_cndmask_b32_e64 v42, v42, v234, s[8:9]
	v_add_u32_e32 v46, 1, v36
	v_add_u32_e32 v47, 1, v42
	v_cndmask_b32_e64 v46, v46, 0, vcc
	v_cndmask_b32_e64 v47, v47, 0, vcc
.Lrank_bit:
	s_or_b32 s22, s20, s18
	s_or_b32 s23, s21, s18
	v_cmp_le_u32_e64 s[24:25], s22, v46
	v_cmp_le_u32_e64 s[26:27], s23, v47
	s_lshr_b32 s18, s18, 1
	s_nop 0
	s_bcnt1_i32_b64 s10, s[24:25]
	s_bcnt1_i32_b64 s11, s[26:27]
	s_cmp_ge_u32 s10, 16
	s_cselect_b32 s20, s22, s20
	s_cmp_ge_u32 s11, 16
	s_cselect_b32 s21, s23, s21
	s_cmp_lg_u32 s18, 0
	s_cbranch_scc1 .Lrank_bit
	v_cmp_lt_u32_e64 s[24:25], s20, v46
	v_cmp_eq_u32_e64 s[12:13], s20, v46
	v_cmp_lt_u32_e64 s[26:27], s21, v47
	v_cmp_eq_u32_e64 s[14:15], s21, v47
	s_nop 1
	s_bcnt1_i32_b64 s10, s[24:25]
	s_bcnt1_i32_b64 s11, s[26:27]
	s_sub_i32 s10, 16, s10
	s_sub_i32 s11, 16, s11
	v_mbcnt_lo_u32_b32 v40, s12, 0
	v_mbcnt_hi_u32_b32 v40, s13, v40
	v_mbcnt_lo_u32_b32 v41, s14, 0
	v_mbcnt_hi_u32_b32 v41, s15, v41
	v_cmp_gt_u32_e64 s[22:23], s10, v40
	v_cmp_gt_u32_e64 s[18:19], s11, v41
	s_nop 1
	s_and_b64 s[12:13], s[12:13], s[22:23]
	s_and_b64 s[14:15], s[14:15], s[18:19]
	s_or_b64 s[12:13], s[12:13], s[24:25]
	s_or_b64 s[14:15], s[14:15], s[26:27]
	s_lshl_b32 s10, s17, 3
	s_add_i32 s10, s10, 0x21c00
	v_mov_b32_e32 v36, s10
	v_mov_b64_e32 v[38:39], s[12:13]
	v_mov_b64_e32 v[40:41], s[14:15]
	s_and_saveexec_b64 s[10:11], s[6:7]
	ds_write_b64 v36, v[38:39]
	ds_write_b64 v36, v[40:41] offset:8
	s_or_b64 exec, exec, s[10:11]
	s_add_i32 s16, s16, 2
	s_cmp_eq_u32 s16, 8
	s_cbranch_scc0 .Lrank_pair
.LBB0_999:
	s_add_i32 s1, 0, 0x21c00
	v_lshl_add_u32 v3, v218, 3, s1
	s_waitcnt lgkmcnt(0)
	s_barrier
	v_lshl_add_u32 v36, v219, 3, s1
	ds_read_b64 v[174:175], v3
	ds_read_b64 v[172:173], v36
